# conversion loop cloned to out2/in3/out3 GEMM phase starts (blocks 128.. convert 8192/10240/8192 queue items in their idle round); topk2/topk3 conversion ranges shrunk
# baseline (speedup 1.0000x reference)
.LBB0_2131:
	s_cmp_gt_i32 s60, 30
	s_cselect_b64 s[4:5], -1, 0
	s_cmp_lt_i32 s61, 31
	s_cselect_b64 s[6:7], -1, 0
	s_or_b64 s[4:5], s[4:5], s[6:7]
	s_and_b64 vcc, exec, s[4:5]
	s_cbranch_vccnz .LBB0_2207
	v_writelane_b32 v129, s3, 0
	v_writelane_b32 v129, s4, 1
	v_writelane_b32 v129, s5, 2
	v_writelane_b32 v129, s6, 3
	v_writelane_b32 v129, s7, 4
	v_writelane_b32 v129, s8, 5
	v_writelane_b32 v129, s9, 6
	v_writelane_b32 v129, s10, 7
	v_writelane_b32 v129, s11, 8
	v_writelane_b32 v129, s12, 9
	v_writelane_b32 v129, s13, 10
	v_writelane_b32 v129, s14, 11
	v_writelane_b32 v129, s15, 12
	v_writelane_b32 v129, s16, 13
	v_writelane_b32 v129, s17, 14
	v_writelane_b32 v129, s18, 15
	v_writelane_b32 v129, s19, 16
	v_writelane_b32 v129, s20, 17
	v_writelane_b32 v129, s21, 18
	v_writelane_b32 v129, s22, 19
	v_writelane_b32 v129, s23, 20
	v_writelane_b32 v129, s24, 21
	v_writelane_b32 v129, s25, 22
	v_writelane_b32 v129, s26, 23
	v_writelane_b32 v129, s27, 24
	v_writelane_b32 v129, s28, 25
	v_writelane_b32 v129, s29, 26
	v_writelane_b32 v129, s30, 27
	v_writelane_b32 v129, s31, 28
	v_writelane_b32 v129, s33, 29
	v_writelane_b32 v129, s34, 30
	v_writelane_b32 v129, s35, 31
	v_writelane_b32 v129, s36, 32
	v_writelane_b32 v129, s37, 33
	v_writelane_b32 v129, s38, 34
	v_writelane_b32 v129, s39, 35
	v_writelane_b32 v129, s41, 36
	v_writelane_b32 v129, s42, 37
	v_writelane_b32 v129, s43, 38
	v_writelane_b32 v129, s45, 39
	v_writelane_b32 v129, s46, 40
	v_writelane_b32 v129, s47, 41
	v_writelane_b32 v129, s49, 42
	v_writelane_b32 v129, s57, 43
	v_writelane_b32 v129, s58, 44
	v_writelane_b32 v129, s59, 45
	v_writelane_b32 v129, s72, 46
	v_writelane_b32 v129, s73, 47
	v_writelane_b32 v129, s76, 48
	v_writelane_b32 v129, s77, 49
	v_writelane_b32 v129, s78, 50
	v_writelane_b32 v129, s79, 51
	v_writelane_b32 v129, s80, 52
	v_writelane_b32 v129, s81, 53
	v_writelane_b32 v129, s84, 54
	v_writelane_b32 v129, s85, 55
	v_writelane_b32 v129, s86, 56
	v_writelane_b32 v129, s87, 57
	v_writelane_b32 v129, s88, 58
	v_writelane_b32 v129, s89, 59
	v_writelane_b32 v129, s90, 60
	v_writelane_b32 v129, s91, 61
	v_writelane_b32 v129, s92, 62
	v_writelane_b32 v129, s93, 63
	s_cmpk_lt_u32 s2, 0x80
	s_cselect_b64 s[4:5], -1, 0
	s_cmpk_gt_u32 s2, 0x7f
	s_cselect_b64 s[10:11], -1, 0
	s_mov_b32 s3, 0x10d00
	s_and_b64 s[6:7], s[10:11], exec
	s_cselect_b32 s12, s3, 0x12d00
	s_mov_b32 s3, 0x12d00
	s_cselect_b32 s13, 0x12d00, s3
	s_add_i32 s14, s54, 0xc000
	s_cmpk_eq_i32 s56, 0x100
	s_cselect_b64 s[6:7], -1, 0
	s_and_b64 s[8:9], s[6:7], exec
	s_cselect_b32 s18, s13, 0
	s_cselect_b32 s19, s12, s14
	s_mov_b32 s3, 0xc000
	s_cmp_ge_u32 s19, s18
	s_mov_b32 s20, 0x12000
	s_waitcnt vmcnt(0)
	s_barrier
	s_cbranch_scc1 .Lcq1_end
	v_readlane_b32 s8, v255, 7
	s_and_b32 s8, s8, 0x3f8
	v_readlane_b32 s13, v255, 6
	s_add_i32 s21, s13, s8
	s_lshl_b32 s22, s21, 1
	s_movk_i32 s12, 0x800
	s_and_b64 s[8:9], s[10:11], exec
	s_cselect_b32 s12, s12, 0x400
	s_and_b64 s[8:9], s[6:7], exec
	s_mul_i32 s8, s13, 0x2200
	s_cselect_b32 s23, s12, s55
	s_add_i32 s25, s8, 0
	v_cndmask_b32_e64 v2, 0, 1, s[4:5]
	v_and_b32_e32 v1, 63, v0
	s_mov_b32 s9, 0
	s_mov_b32 s24, 0x10000
	s_add_i32 s25, s25, 0x10000
	s_and_b64 s[10:11], s[10:11], s[6:7]
	v_cmp_ne_u32_e64 s[4:5], 1, v2
	v_mov_b32_e32 v3, 0
	s_movk_i32 s26, 0x2000
	s_movk_i32 s27, 0x4000
	s_movk_i32 s28, 0x6000
	s_mov_b32 s29, 0x8000
	s_mov_b32 s30, 0xa000
	s_mov_b32 s31, 0xe000
	s_mov_b32 s34, 0x14000
	s_mov_b32 s35, 0x16000
	s_mov_b32 s36, 0x18000
	s_mov_b32 s37, 0x1a000
	s_mov_b32 s38, 0x1c000
	s_mov_b32 s39, 0x1e000
	s_mov_b32 s41, 0x20000
	s_mov_b32 s42, 0x22000
	s_mov_b32 s43, 0x24000
	s_mov_b32 s45, 0x26000
	s_mov_b32 s46, 0x28000
	s_mov_b32 s47, 0x2a000
	s_mov_b32 s49, 0x2c000
	s_mov_b32 s57, 0x2e000
	s_mov_b32 s58, 0x30000
	s_mov_b32 s59, 0x32000
	s_mov_b32 s72, 0x34000
	s_mov_b32 s73, 0x36000
	s_mov_b32 s78, 0x38000
	s_mov_b32 s79, 0x3a000
	s_mov_b32 s84, 0x3c000
	s_mov_b32 s85, 0x3e000
	s_movk_i32 s86, 0x84
	s_branch .Lcq1_2352

.Lcq1_end:
	s_waitcnt vmcnt(0) lgkmcnt(0)
	s_barrier
	v_readlane_b32 s3, v129, 0
	v_readlane_b32 s4, v129, 1
	v_readlane_b32 s5, v129, 2
	v_readlane_b32 s6, v129, 3
	v_readlane_b32 s7, v129, 4
	v_readlane_b32 s8, v129, 5
	v_readlane_b32 s9, v129, 6
	v_readlane_b32 s10, v129, 7
	v_readlane_b32 s11, v129, 8
	v_readlane_b32 s12, v129, 9
	v_readlane_b32 s13, v129, 10
	v_readlane_b32 s14, v129, 11
	v_readlane_b32 s15, v129, 12
	v_readlane_b32 s16, v129, 13
	v_readlane_b32 s17, v129, 14
	v_readlane_b32 s18, v129, 15
	v_readlane_b32 s19, v129, 16
	v_readlane_b32 s20, v129, 17
	v_readlane_b32 s21, v129, 18
	v_readlane_b32 s22, v129, 19
	v_readlane_b32 s23, v129, 20
	v_readlane_b32 s24, v129, 21
	v_readlane_b32 s25, v129, 22
	v_readlane_b32 s26, v129, 23
	v_readlane_b32 s27, v129, 24
	v_readlane_b32 s28, v129, 25
	v_readlane_b32 s29, v129, 26
	v_readlane_b32 s30, v129, 27
	v_readlane_b32 s31, v129, 28
	v_readlane_b32 s33, v129, 29
	v_readlane_b32 s34, v129, 30
	v_readlane_b32 s35, v129, 31
	v_readlane_b32 s36, v129, 32
	v_readlane_b32 s37, v129, 33
	v_readlane_b32 s38, v129, 34
	v_readlane_b32 s39, v129, 35
	v_readlane_b32 s41, v129, 36
	v_readlane_b32 s42, v129, 37
	v_readlane_b32 s43, v129, 38
	v_readlane_b32 s45, v129, 39
	v_readlane_b32 s46, v129, 40
	v_readlane_b32 s47, v129, 41
	v_readlane_b32 s49, v129, 42
	v_readlane_b32 s57, v129, 43
	v_readlane_b32 s58, v129, 44
	v_readlane_b32 s59, v129, 45
	v_readlane_b32 s72, v129, 46
	v_readlane_b32 s73, v129, 47
	v_readlane_b32 s76, v129, 48
	v_readlane_b32 s77, v129, 49
	v_readlane_b32 s78, v129, 50
	v_readlane_b32 s79, v129, 51
	v_readlane_b32 s80, v129, 52
	v_readlane_b32 s81, v129, 53
	v_readlane_b32 s84, v129, 54
	v_readlane_b32 s85, v129, 55
	v_readlane_b32 s86, v129, 56
	v_readlane_b32 s87, v129, 57
	v_readlane_b32 s88, v129, 58
	v_readlane_b32 s89, v129, 59
	v_readlane_b32 s90, v129, 60
	v_readlane_b32 s91, v129, 61
	v_readlane_b32 s92, v129, 62
	v_readlane_b32 s93, v129, 63
	s_waitcnt vmcnt(0)
	v_mov_b32_e32 v2, v0
	s_cmpk_gt_i32 s2, 0x1ff
	v_readfirstlane_b32 s3, v2
	s_cbranch_scc1 .LBB0_2157
	s_ashr_i32 s14, s2, 31
	s_lshr_b32 s4, s14, 29
	s_add_i32 s7, s2, s4
	s_and_b32 s4, s7, -8
	s_sub_i32 s8, s2, s4
	s_cmp_gt_i32 s8, -1
	s_cbranch_scc0 .LBB0_2135
	s_lshl_b32 s6, s8, 6
	s_cbranch_execz .LBB0_2136
	s_branch .LBB0_2137

.LBB0_2349:
	s_cmpk_lt_u32 s2, 0x80
	s_cselect_b64 s[4:5], -1, 0
	s_cmpk_gt_u32 s2, 0x7f
	s_cselect_b64 s[10:11], -1, 0
	s_mov_b32 s3, 0x12d00
	s_and_b64 s[6:7], s[10:11], exec
	s_cselect_b32 s12, s3, 0x12d00
	s_mov_b32 s3, 0x12d00
	s_cselect_b32 s13, 0x12d00, s3
	s_add_i32 s14, s54, 0xc000
	s_cmpk_eq_i32 s56, 0x100
	s_cselect_b64 s[6:7], -1, 0
	s_and_b64 s[8:9], s[6:7], exec
	s_cselect_b32 s18, s13, 0x12000
	s_cselect_b32 s19, s12, s14
	s_mov_b32 s3, 0xc000
	s_cmp_ge_u32 s19, s18
	s_mov_b32 s20, 0x12000
	s_waitcnt vmcnt(0)
	s_barrier
	s_cbranch_scc1 .LBB0_2364
	v_readlane_b32 s8, v255, 7
	s_and_b32 s8, s8, 0x3f8
	v_readlane_b32 s13, v255, 6
	s_add_i32 s21, s13, s8
	s_lshl_b32 s22, s21, 1
	s_movk_i32 s12, 0x800
	s_and_b64 s[8:9], s[10:11], exec
	s_cselect_b32 s12, s12, 0x400
	s_and_b64 s[8:9], s[6:7], exec
	s_mul_i32 s8, s13, 0x2200
	s_cselect_b32 s23, s12, s55
	s_add_i32 s25, s8, 0
	v_cndmask_b32_e64 v2, 0, 1, s[4:5]
	v_and_b32_e32 v1, 63, v0
	s_mov_b32 s9, 0
	s_mov_b32 s24, 0x10000
	s_add_i32 s25, s25, 0x10000
	s_and_b64 s[10:11], s[10:11], s[6:7]
	v_cmp_ne_u32_e64 s[4:5], 1, v2
	v_mov_b32_e32 v3, 0
	s_movk_i32 s26, 0x2000
	s_movk_i32 s27, 0x4000
	s_movk_i32 s28, 0x6000
	s_mov_b32 s29, 0x8000
	s_mov_b32 s30, 0xa000
	s_mov_b32 s31, 0xe000
	s_mov_b32 s34, 0x14000
	s_mov_b32 s35, 0x16000
	s_mov_b32 s36, 0x18000
	s_mov_b32 s37, 0x1a000
	s_mov_b32 s38, 0x1c000
	s_mov_b32 s39, 0x1e000
	s_mov_b32 s41, 0x20000
	s_mov_b32 s42, 0x22000
	s_mov_b32 s43, 0x24000
	s_mov_b32 s45, 0x26000
	s_mov_b32 s46, 0x28000
	s_mov_b32 s47, 0x2a000
	s_mov_b32 s49, 0x2c000
	s_mov_b32 s57, 0x2e000
	s_mov_b32 s58, 0x30000
	s_mov_b32 s59, 0x32000
	s_mov_b32 s72, 0x34000
	s_mov_b32 s73, 0x36000
	s_mov_b32 s78, 0x38000
	s_mov_b32 s79, 0x3a000
	s_mov_b32 s84, 0x3c000
	s_mov_b32 s85, 0x3e000
	s_movk_i32 s86, 0x84
	s_branch .LBB0_2352

.LBB0_2670:
	s_cmp_lt_i32 s61, 39
	s_cbranch_scc1 .LBB0_3322
	s_cmp_gt_i32 s60, 38
	s_cbranch_scc1 .LBB0_2740
	v_writelane_b32 v129, s3, 0
	v_writelane_b32 v129, s4, 1
	v_writelane_b32 v129, s5, 2
	v_writelane_b32 v129, s6, 3
	v_writelane_b32 v129, s7, 4
	v_writelane_b32 v129, s8, 5
	v_writelane_b32 v129, s9, 6
	v_writelane_b32 v129, s10, 7
	v_writelane_b32 v129, s11, 8
	v_writelane_b32 v129, s12, 9
	v_writelane_b32 v129, s13, 10
	v_writelane_b32 v129, s14, 11
	v_writelane_b32 v129, s15, 12
	v_writelane_b32 v129, s16, 13
	v_writelane_b32 v129, s17, 14
	v_writelane_b32 v129, s18, 15
	v_writelane_b32 v129, s19, 16
	v_writelane_b32 v129, s20, 17
	v_writelane_b32 v129, s21, 18
	v_writelane_b32 v129, s22, 19
	v_writelane_b32 v129, s23, 20
	v_writelane_b32 v129, s24, 21
	v_writelane_b32 v129, s25, 22
	v_writelane_b32 v129, s26, 23
	v_writelane_b32 v129, s27, 24
	v_writelane_b32 v129, s28, 25
	v_writelane_b32 v129, s29, 26
	v_writelane_b32 v129, s30, 27
	v_writelane_b32 v129, s31, 28
	v_writelane_b32 v129, s33, 29
	v_writelane_b32 v129, s34, 30
	v_writelane_b32 v129, s35, 31
	v_writelane_b32 v129, s36, 32
	v_writelane_b32 v129, s37, 33
	v_writelane_b32 v129, s38, 34
	v_writelane_b32 v129, s39, 35
	v_writelane_b32 v129, s41, 36
	v_writelane_b32 v129, s42, 37
	v_writelane_b32 v129, s43, 38
	v_writelane_b32 v129, s45, 39
	v_writelane_b32 v129, s46, 40
	v_writelane_b32 v129, s47, 41
	v_writelane_b32 v129, s49, 42
	v_writelane_b32 v129, s57, 43
	v_writelane_b32 v129, s58, 44
	v_writelane_b32 v129, s59, 45
	v_writelane_b32 v129, s72, 46
	v_writelane_b32 v129, s73, 47
	v_writelane_b32 v129, s76, 48
	v_writelane_b32 v129, s77, 49
	v_writelane_b32 v129, s78, 50
	v_writelane_b32 v129, s79, 51
	v_writelane_b32 v129, s80, 52
	v_writelane_b32 v129, s81, 53
	v_writelane_b32 v129, s84, 54
	v_writelane_b32 v129, s85, 55
	v_writelane_b32 v129, s86, 56
	v_writelane_b32 v129, s87, 57
	v_writelane_b32 v129, s88, 58
	v_writelane_b32 v129, s89, 59
	v_writelane_b32 v129, s90, 60
	v_writelane_b32 v129, s91, 61
	v_writelane_b32 v129, s92, 62
	v_writelane_b32 v129, s93, 63
	s_cmpk_lt_u32 s2, 0x80
	s_cselect_b64 s[4:5], -1, 0
	s_cmpk_gt_u32 s2, 0x7f
	s_cselect_b64 s[10:11], -1, 0
	s_mov_b32 s3, 0x12d00
	s_and_b64 s[6:7], s[10:11], exec
	s_cselect_b32 s12, s3, 0x15500
	s_mov_b32 s3, 0x15500
	s_cselect_b32 s13, 0x15500, s3
	s_add_i32 s14, s54, 0xc000
	s_cmpk_eq_i32 s56, 0x100
	s_cselect_b64 s[6:7], -1, 0
	s_and_b64 s[8:9], s[6:7], exec
	s_cselect_b32 s18, s13, 0
	s_cselect_b32 s19, s12, s14
	s_mov_b32 s3, 0xc000
	s_cmp_ge_u32 s19, s18
	s_mov_b32 s20, 0x12000
	s_waitcnt vmcnt(0)
	s_barrier
	s_cbranch_scc1 .Lcq2_end
	v_readlane_b32 s8, v255, 7
	s_and_b32 s8, s8, 0x3f8
	v_readlane_b32 s13, v255, 6
	s_add_i32 s21, s13, s8
	s_lshl_b32 s22, s21, 1
	s_movk_i32 s12, 0x800
	s_and_b64 s[8:9], s[10:11], exec
	s_cselect_b32 s12, s12, 0x400
	s_and_b64 s[8:9], s[6:7], exec
	s_mul_i32 s8, s13, 0x2200
	s_cselect_b32 s23, s12, s55
	s_add_i32 s25, s8, 0
	v_cndmask_b32_e64 v2, 0, 1, s[4:5]
	v_and_b32_e32 v1, 63, v0
	s_mov_b32 s9, 0
	s_mov_b32 s24, 0x10000
	s_add_i32 s25, s25, 0x10000
	s_and_b64 s[10:11], s[10:11], s[6:7]
	v_cmp_ne_u32_e64 s[4:5], 1, v2
	v_mov_b32_e32 v3, 0
	s_movk_i32 s26, 0x2000
	s_movk_i32 s27, 0x4000
	s_movk_i32 s28, 0x6000
	s_mov_b32 s29, 0x8000
	s_mov_b32 s30, 0xa000
	s_mov_b32 s31, 0xe000
	s_mov_b32 s34, 0x14000
	s_mov_b32 s35, 0x16000
	s_mov_b32 s36, 0x18000
	s_mov_b32 s37, 0x1a000
	s_mov_b32 s38, 0x1c000
	s_mov_b32 s39, 0x1e000
	s_mov_b32 s41, 0x20000
	s_mov_b32 s42, 0x22000
	s_mov_b32 s43, 0x24000
	s_mov_b32 s45, 0x26000
	s_mov_b32 s46, 0x28000
	s_mov_b32 s47, 0x2a000
	s_mov_b32 s49, 0x2c000
	s_mov_b32 s57, 0x2e000
	s_mov_b32 s58, 0x30000
	s_mov_b32 s59, 0x32000
	s_mov_b32 s72, 0x34000
	s_mov_b32 s73, 0x36000
	s_mov_b32 s78, 0x38000
	s_mov_b32 s79, 0x3a000
	s_mov_b32 s84, 0x3c000
	s_mov_b32 s85, 0x3e000
	s_movk_i32 s86, 0x84
	s_branch .Lcq2_2352

.Lcq2_end:
	s_waitcnt vmcnt(0) lgkmcnt(0)
	s_barrier
	v_readlane_b32 s3, v129, 0
	v_readlane_b32 s4, v129, 1
	v_readlane_b32 s5, v129, 2
	v_readlane_b32 s6, v129, 3
	v_readlane_b32 s7, v129, 4
	v_readlane_b32 s8, v129, 5
	v_readlane_b32 s9, v129, 6
	v_readlane_b32 s10, v129, 7
	v_readlane_b32 s11, v129, 8
	v_readlane_b32 s12, v129, 9
	v_readlane_b32 s13, v129, 10
	v_readlane_b32 s14, v129, 11
	v_readlane_b32 s15, v129, 12
	v_readlane_b32 s16, v129, 13
	v_readlane_b32 s17, v129, 14
	v_readlane_b32 s18, v129, 15
	v_readlane_b32 s19, v129, 16
	v_readlane_b32 s20, v129, 17
	v_readlane_b32 s21, v129, 18
	v_readlane_b32 s22, v129, 19
	v_readlane_b32 s23, v129, 20
	v_readlane_b32 s24, v129, 21
	v_readlane_b32 s25, v129, 22
	v_readlane_b32 s26, v129, 23
	v_readlane_b32 s27, v129, 24
	v_readlane_b32 s28, v129, 25
	v_readlane_b32 s29, v129, 26
	v_readlane_b32 s30, v129, 27
	v_readlane_b32 s31, v129, 28
	v_readlane_b32 s33, v129, 29
	v_readlane_b32 s34, v129, 30
	v_readlane_b32 s35, v129, 31
	v_readlane_b32 s36, v129, 32
	v_readlane_b32 s37, v129, 33
	v_readlane_b32 s38, v129, 34
	v_readlane_b32 s39, v129, 35
	v_readlane_b32 s41, v129, 36
	v_readlane_b32 s42, v129, 37
	v_readlane_b32 s43, v129, 38
	v_readlane_b32 s45, v129, 39
	v_readlane_b32 s46, v129, 40
	v_readlane_b32 s47, v129, 41
	v_readlane_b32 s49, v129, 42
	v_readlane_b32 s57, v129, 43
	v_readlane_b32 s58, v129, 44
	v_readlane_b32 s59, v129, 45
	v_readlane_b32 s72, v129, 46
	v_readlane_b32 s73, v129, 47
	v_readlane_b32 s76, v129, 48
	v_readlane_b32 s77, v129, 49
	v_readlane_b32 s78, v129, 50
	v_readlane_b32 s79, v129, 51
	v_readlane_b32 s80, v129, 52
	v_readlane_b32 s81, v129, 53
	v_readlane_b32 s84, v129, 54
	v_readlane_b32 s85, v129, 55
	v_readlane_b32 s86, v129, 56
	v_readlane_b32 s87, v129, 57
	v_readlane_b32 s88, v129, 58
	v_readlane_b32 s89, v129, 59
	v_readlane_b32 s90, v129, 60
	v_readlane_b32 s91, v129, 61
	v_readlane_b32 s92, v129, 62
	v_readlane_b32 s93, v129, 63
	s_waitcnt vmcnt(0)
	v_mov_b32_e32 v2, v0
	s_cmpk_gt_i32 s2, 0x5ff
	v_readfirstlane_b32 s3, v2
	s_cbranch_scc1 .LBB0_2690
	v_bfe_i32 v4, v2, 27, 1
	v_lshlrev_b32_e32 v1, 4, v2
	v_lshrrev_b32_e32 v4, 22, v4
	v_add_u32_e32 v4, v1, v4
	v_and_b32_e32 v4, 0xfffffc00, v4
	v_sub_u32_e32 v1, v1, v4
	v_ashrrev_i32_e32 v3, 31, v2
	v_lshrrev_b32_e32 v4, 4, v1
	v_lshrrev_b32_e32 v3, 26, v3
	v_bitop3_b32 v1, v4, v1, 32 bitop3:0x6c
	s_add_u32 s8, s52, 0x1100000
	v_add_u32_e32 v3, v2, v3
	v_ashrrev_i32_e32 v5, 31, v1
	s_addc_u32 s6, s53, 0
	v_ashrrev_i32_e32 v3, 6, v3
	v_lshrrev_b32_e32 v5, 26, v5
	s_ashr_i32 s20, s2, 31
	v_lshlrev_b32_e32 v4, 3, v3
	v_add_u32_e32 v5, v1, v5
	s_lshr_b32 s7, s20, 29
	v_readlane_b32 s10, v255, 8
	v_and_b32_e32 v4, -16, v4
	v_ashrrev_i32_e32 v6, 6, v5
	s_add_i32 s7, s2, s7
	s_ashr_i32 s4, s3, 6
	v_readlane_b32 s11, v255, 9
	v_add_u32_e32 v4, v6, v4
	v_and_b32_e32 v6, 3, v6
	s_mov_b32 s5, 0x1fffe0
	s_ashr_i32 s12, s7, 3
	s_and_b32 s7, s7, -8
	s_and_b32 s41, s11, 0xffff
	v_and_or_b32 v6, v4, s5, v6
	s_ashr_i32 s5, s3, 8
	s_and_b32 s9, s6, 0xffff
	s_lshl_b32 s6, s4, 10
	s_sub_i32 s7, s2, s7
	s_cmp_lt_i32 s7, 0
	s_movk_i32 s21, 0xc1
	s_cselect_b32 s13, s21, 0xc0
	s_mul_i32 s7, s13, s7
	s_add_i32 s7, s7, s12
	s_mul_hi_i32 s12, s7, 0x2aaaaaab
	s_lshr_b32 s13, s12, 31
	s_ashr_i32 s12, s12, 4
	s_add_i32 s12, s12, s13
	s_lshl_b32 s13, s12, 3
	s_mulk_i32 s12, 0x60
	s_sub_i32 s7, s7, s12
	s_bfe_i32 s12, s7, 0x80000
	s_bfe_u32 s12, s12, 0x3000c
	s_add_i32 s12, s7, s12
	s_bfe_i32 s14, s12, 0x80000
	s_and_b32 s12, s12, 0xf8
	s_sub_i32 s7, s7, s12
	s_sext_i32_i8 s7, s7
	s_add_i32 s78, s13, s7
	s_ashr_i32 s7, s78, 31
	v_and_b32_e32 v5, 0xc0, v5
	s_lshr_b32 s7, s7, 12
	v_sub_u32_e32 v1, v1, v5
	v_mov_b32_e32 v5, 1
	s_add_i32 s7, s78, s7
	v_lshlrev_b32_e32 v3, 5, v3
	v_ashrrev_i16_sdwa v1, v5, sext(v1) dst_sel:DWORD dst_unused:UNUSED_PAD src0_sel:DWORD src1_sel:BYTE_0
	v_lshlrev_b32_e32 v5, 1, v4
	v_lshrrev_b32_e32 v7, 2, v4
	s_sext_i32_i16 s14, s14
	s_ashr_i32 s7, s7, 20
	v_and_b32_e32 v3, 32, v3
	v_bfe_i32 v1, v1, 0, 16
	v_and_b32_e32 v5, 24, v5
	v_and_b32_e32 v7, 4, v7
	s_ashr_i32 s73, s14, 3
	s_mul_i32 s7, s7, 12
	s_add_i32 s22, s6, 0
	s_mov_b32 s43, 0x20000
	s_brev_b32 s42, -2
	v_or3_b32 v5, v6, v7, v5
	v_add_lshl_u32 v3, v3, v1, 1
	s_add_i32 s7, s7, s73
	s_add_i32 s23, s22, 0x10000
	v_lshl_add_u32 v144, v5, 11, v3
	s_mov_b32 s10, s42
	s_mov_b32 s11, s43
	s_lshl_b32 s79, s7, 19
	s_mov_b32 m0, s23
	s_add_i32 s24, s22, 0x12000
	s_mov_b32 s100, 0
	buffer_load_dwordx4 v144, s[8:11], s79 offen lds
	s_or_b32 s6, s79, 0x20000
	s_mov_b32 m0, s24
	v_lshl_add_u32 v1, v4, 11, v3
	buffer_load_dwordx4 v144, s[8:11], s6 offen lds
	s_lshl_b32 s84, s78, 19
	s_mov_b32 m0, s22
	s_add_i32 s25, s22, 0x2000
	buffer_load_dwordx4 v1, s[40:43], s84 offen lds
	s_or_b32 s6, s84, 0x20000
	s_mov_b32 m0, s25
	s_add_i32 s26, s22, 0x14000
	buffer_load_dwordx4 v1, s[40:43], s6 offen lds
	s_or_b32 s6, s79, 0x40000
	s_mov_b32 m0, s26
	s_add_i32 s27, s22, 0x16000
	buffer_load_dwordx4 v144, s[8:11], s6 offen lds
	s_or_b32 s6, s79, 0x60000
	s_mov_b32 m0, s27
	s_add_i32 s28, s22, 0x4000
	buffer_load_dwordx4 v144, s[8:11], s6 offen lds
	s_or_b32 s6, s84, 0x40000
	s_mov_b32 m0, s28
	s_add_i32 s29, s22, 0x6000
	buffer_load_dwordx4 v1, s[40:43], s6 offen lds
	s_or_b32 s6, s84, 0x60000
	s_mov_b32 m0, s29
	s_cmp_lg_u32 s5, 1
	buffer_load_dwordx4 v1, s[40:43], s6 offen lds
	s_mov_b32 s30, 0
	s_cbranch_scc1 .LBB0_2675
	s_barrier

.LBB0_2807:
	s_cmp_gt_i32 s60, 42
	s_cselect_b64 s[4:5], -1, 0
	s_cmp_lt_i32 s61, 43
	s_cselect_b64 s[6:7], -1, 0
	s_or_b64 s[4:5], s[4:5], s[6:7]
	s_and_b64 vcc, exec, s[4:5]
	s_cbranch_vccnz .LBB0_2883
	v_writelane_b32 v129, s3, 0
	v_writelane_b32 v129, s4, 1
	v_writelane_b32 v129, s5, 2
	v_writelane_b32 v129, s6, 3
	v_writelane_b32 v129, s7, 4
	v_writelane_b32 v129, s8, 5
	v_writelane_b32 v129, s9, 6
	v_writelane_b32 v129, s10, 7
	v_writelane_b32 v129, s11, 8
	v_writelane_b32 v129, s12, 9
	v_writelane_b32 v129, s13, 10
	v_writelane_b32 v129, s14, 11
	v_writelane_b32 v129, s15, 12
	v_writelane_b32 v129, s16, 13
	v_writelane_b32 v129, s17, 14
	v_writelane_b32 v129, s18, 15
	v_writelane_b32 v129, s19, 16
	v_writelane_b32 v129, s20, 17
	v_writelane_b32 v129, s21, 18
	v_writelane_b32 v129, s22, 19
	v_writelane_b32 v129, s23, 20
	v_writelane_b32 v129, s24, 21
	v_writelane_b32 v129, s25, 22
	v_writelane_b32 v129, s26, 23
	v_writelane_b32 v129, s27, 24
	v_writelane_b32 v129, s28, 25
	v_writelane_b32 v129, s29, 26
	v_writelane_b32 v129, s30, 27
	v_writelane_b32 v129, s31, 28
	v_writelane_b32 v129, s33, 29
	v_writelane_b32 v129, s34, 30
	v_writelane_b32 v129, s35, 31
	v_writelane_b32 v129, s36, 32
	v_writelane_b32 v129, s37, 33
	v_writelane_b32 v129, s38, 34
	v_writelane_b32 v129, s39, 35
	v_writelane_b32 v129, s41, 36
	v_writelane_b32 v129, s42, 37
	v_writelane_b32 v129, s43, 38
	v_writelane_b32 v129, s45, 39
	v_writelane_b32 v129, s46, 40
	v_writelane_b32 v129, s47, 41
	v_writelane_b32 v129, s49, 42
	v_writelane_b32 v129, s57, 43
	v_writelane_b32 v129, s58, 44
	v_writelane_b32 v129, s59, 45
	v_writelane_b32 v129, s72, 46
	v_writelane_b32 v129, s73, 47
	v_writelane_b32 v129, s76, 48
	v_writelane_b32 v129, s77, 49
	v_writelane_b32 v129, s78, 50
	v_writelane_b32 v129, s79, 51
	v_writelane_b32 v129, s80, 52
	v_writelane_b32 v129, s81, 53
	v_writelane_b32 v129, s84, 54
	v_writelane_b32 v129, s85, 55
	v_writelane_b32 v129, s86, 56
	v_writelane_b32 v129, s87, 57
	v_writelane_b32 v129, s88, 58
	v_writelane_b32 v129, s89, 59
	v_writelane_b32 v129, s90, 60
	v_writelane_b32 v129, s91, 61
	v_writelane_b32 v129, s92, 62
	v_writelane_b32 v129, s93, 63
	s_cmpk_lt_u32 s2, 0x80
	s_cselect_b64 s[4:5], -1, 0
	s_cmpk_gt_u32 s2, 0x7f
	s_cselect_b64 s[10:11], -1, 0
	s_mov_b32 s3, 0x15500
	s_and_b64 s[6:7], s[10:11], exec
	s_cselect_b32 s12, s3, 0x17500
	s_mov_b32 s3, 0x17500
	s_cselect_b32 s13, 0x17500, s3
	s_add_i32 s14, s54, 0xc000
	s_cmpk_eq_i32 s56, 0x100
	s_cselect_b64 s[6:7], -1, 0
	s_and_b64 s[8:9], s[6:7], exec
	s_cselect_b32 s18, s13, 0
	s_cselect_b32 s19, s12, s14
	s_mov_b32 s3, 0xc000
	s_cmp_ge_u32 s19, s18
	s_mov_b32 s20, 0x12000
	s_waitcnt vmcnt(0)
	s_barrier
	s_cbranch_scc1 .Lcq3_end
	v_readlane_b32 s8, v255, 7
	s_and_b32 s8, s8, 0x3f8
	v_readlane_b32 s13, v255, 6
	s_add_i32 s21, s13, s8
	s_lshl_b32 s22, s21, 1
	s_movk_i32 s12, 0x800
	s_and_b64 s[8:9], s[10:11], exec
	s_cselect_b32 s12, s12, 0x400
	s_and_b64 s[8:9], s[6:7], exec
	s_mul_i32 s8, s13, 0x2200
	s_cselect_b32 s23, s12, s55
	s_add_i32 s25, s8, 0
	v_cndmask_b32_e64 v2, 0, 1, s[4:5]
	v_and_b32_e32 v1, 63, v0
	s_mov_b32 s9, 0
	s_mov_b32 s24, 0x10000
	s_add_i32 s25, s25, 0x10000
	s_and_b64 s[10:11], s[10:11], s[6:7]
	v_cmp_ne_u32_e64 s[4:5], 1, v2
	v_mov_b32_e32 v3, 0
	s_movk_i32 s26, 0x2000
	s_movk_i32 s27, 0x4000
	s_movk_i32 s28, 0x6000
	s_mov_b32 s29, 0x8000
	s_mov_b32 s30, 0xa000
	s_mov_b32 s31, 0xe000
	s_mov_b32 s34, 0x14000
	s_mov_b32 s35, 0x16000
	s_mov_b32 s36, 0x18000
	s_mov_b32 s37, 0x1a000
	s_mov_b32 s38, 0x1c000
	s_mov_b32 s39, 0x1e000
	s_mov_b32 s41, 0x20000
	s_mov_b32 s42, 0x22000
	s_mov_b32 s43, 0x24000
	s_mov_b32 s45, 0x26000
	s_mov_b32 s46, 0x28000
	s_mov_b32 s47, 0x2a000
	s_mov_b32 s49, 0x2c000
	s_mov_b32 s57, 0x2e000
	s_mov_b32 s58, 0x30000
	s_mov_b32 s59, 0x32000
	s_mov_b32 s72, 0x34000
	s_mov_b32 s73, 0x36000
	s_mov_b32 s78, 0x38000
	s_mov_b32 s79, 0x3a000
	s_mov_b32 s84, 0x3c000
	s_mov_b32 s85, 0x3e000
	s_movk_i32 s86, 0x84
	s_branch .Lcq3_2352

.LBB0_3025:
	s_cmpk_lt_u32 s2, 0x80
	s_cselect_b64 s[4:5], -1, 0
	s_cmpk_gt_u32 s2, 0x7f
	s_cselect_b64 s[10:11], -1, 0
	s_mov_b32 s3, 0x17500
	s_and_b64 s[6:7], s[10:11], exec
	s_cselect_b32 s12, s3, 0x18000
	s_add_i32 s13, s54, 0x12000
	s_cmpk_eq_i32 s56, 0x100
	s_cselect_b64 s[6:7], -1, 0
	s_and_b64 s[8:9], s[6:7], exec
	s_cselect_b32 s18, s12, s13
	s_and_b64 s[8:9], s[10:11], s[6:7]
	s_mov_b32 s19, 0x18000
	s_and_b64 s[12:13], s[8:9], exec
	s_cselect_b32 s20, 0x18000, s19
	s_mov_b32 s3, 0x12000
	s_cmp_ge_u32 s18, s20
	s_waitcnt vmcnt(0)
	s_barrier
	s_cbranch_scc1 .LBB0_3040
	v_readlane_b32 s12, v255, 7
	s_and_b32 s12, s12, 0x3f8
	v_readlane_b32 s13, v255, 6
	s_add_i32 s21, s13, s12
	s_lshl_b32 s22, s21, 1
	s_movk_i32 s12, 0x800
	s_and_b64 s[10:11], s[10:11], exec
	s_cselect_b32 s12, s12, 0x400
	s_and_b64 s[10:11], s[6:7], exec
	s_mul_i32 s10, s13, 0x2200
	s_cselect_b32 s23, s12, s55
	s_add_i32 s25, s10, 0
	v_cndmask_b32_e64 v2, 0, 1, s[4:5]
	s_mov_b32 s11, 0
	s_mov_b32 s24, 0x10000
	s_add_i32 s25, s25, 0x10000
	v_cmp_ne_u32_e64 s[4:5], 1, v2
	v_mov_b32_e32 v3, 0
	s_movk_i32 s26, 0x2000
	s_movk_i32 s27, 0x4000
	s_movk_i32 s28, 0x6000
	s_mov_b32 s29, 0x8000
	s_mov_b32 s30, 0xa000
	s_mov_b32 s31, 0xc000
	s_mov_b32 s34, 0xe000
	s_mov_b32 s35, 0x14000
	s_mov_b32 s36, 0x16000
	s_mov_b32 s37, 0x1a000
	s_mov_b32 s38, 0x1c000
	s_mov_b32 s39, 0x1e000
	s_mov_b32 s41, 0x20000
	s_mov_b32 s42, 0x22000
	s_mov_b32 s43, 0x24000
	s_mov_b32 s45, 0x26000
	s_mov_b32 s46, 0x28000
	s_mov_b32 s47, 0x2a000
	s_mov_b32 s50, 0x2c000
	s_mov_b32 s51, 0x2e000
	s_mov_b32 s57, 0x30000
	s_mov_b32 s58, 0x32000
	s_mov_b32 s59, 0x34000
	s_mov_b32 s72, 0x36000
	s_mov_b32 s73, 0x38000
	s_mov_b32 s76, 0x3a000
	s_mov_b32 s77, 0x3c000
	s_mov_b32 s78, 0x3e000
	s_movk_i32 s79, 0x84
	s_movk_i32 s80, 0xc8
	s_branch .LBB0_3028
